# v029: conv_item_p depthwise conv31 with v_pk_fma_f32 (token pairs share the tap weight via op_sel broadcast, input values kept as aligned pairs): 248 packed FMAs instead of 496 scalar, same accumulati
# speedup vs baseline: 1.0070x; 1.0060x over previous
.LBB0_562:
	ds_read_u16 v50, v86 offset:32768
	ds_read_u16 v51, v86 offset:33792
	ds_read_u16 v52, v86 offset:34816
	ds_read_u16 v53, v86 offset:35840
	ds_read_u16 v55, v86 offset:36864
	ds_read_u16 v56, v86 offset:37888
	ds_read_u16 v57, v86 offset:38912
	ds_read_u16 v58, v86 offset:39936
	ds_read_u16 v59, v86 offset:40960
	ds_read_u16 v77, v86 offset:41984
	ds_read_u16 v78, v86 offset:43008
	ds_read_u16 v79, v86 offset:44032
	ds_read_u16 v80, v86 offset:45056
	ds_read_u16 v76, v86 offset:46080
	ds_read_u16 v54, v86 offset:47104
	ds_read_u16 v81, v86 offset:48128
	ds_read_u16 v104, v86 offset:31744
	ds_read_u16 v105, v87 offset:15360
	ds_read_u16 v16, v89
	ds_read_u16 v17, v89 offset:1024
	ds_read_u16 v18, v89 offset:2048
	ds_read_u16 v19, v89 offset:3072
	ds_read_u16 v20, v89 offset:4096
	ds_read_u16 v21, v89 offset:5120
	ds_read_u16 v22, v89 offset:6144
	ds_read_u16 v23, v89 offset:7168
	ds_read_u16 v24, v89 offset:8192
	ds_read_u16 v25, v89 offset:9216
	ds_read_u16 v26, v89 offset:10240
	ds_read_u16 v27, v89 offset:11264
	ds_read_u16 v98, v89 offset:12288
	ds_read_u16 v99, v89 offset:13312
	ds_read_u16 v100, v89 offset:14336
	ds_read_u16 v101, v89 offset:15360
	s_waitcnt lgkmcnt(15)
	v_lshlrev_b32_e32 v122, 16, v16
	s_waitcnt lgkmcnt(14)
	v_lshlrev_b32_e32 v123, 16, v17
	v_lshlrev_b32_e32 v102, 16, v17
	v_pk_fma_f32 v[106:107], v[150:151], v[122:123], v[60:61] op_sel:[0,0,0] op_sel_hi:[0,1,0]
	s_waitcnt lgkmcnt(13)
	v_lshlrev_b32_e32 v103, 16, v18
	v_lshlrev_b32_e32 v122, 16, v18
	v_pk_fma_f32 v[106:107], v[148:149], v[102:103], v[106:107] op_sel:[1,0,0] op_sel_hi:[1,1,1]
	s_waitcnt lgkmcnt(12)
	v_lshlrev_b32_e32 v123, 16, v19
	v_lshlrev_b32_e32 v102, 16, v19
	v_pk_fma_f32 v[106:107], v[148:149], v[122:123], v[106:107] op_sel:[0,0,0] op_sel_hi:[0,1,1]
	v_pk_fma_f32 v[108:109], v[150:151], v[122:123], v[60:61] op_sel:[0,0,0] op_sel_hi:[0,1,0]
	s_waitcnt lgkmcnt(11)
	v_lshlrev_b32_e32 v103, 16, v20
	v_lshlrev_b32_e32 v122, 16, v20
	v_pk_fma_f32 v[106:107], v[146:147], v[102:103], v[106:107] op_sel:[1,0,0] op_sel_hi:[1,1,1]
	v_pk_fma_f32 v[108:109], v[148:149], v[102:103], v[108:109] op_sel:[1,0,0] op_sel_hi:[1,1,1]
	s_waitcnt lgkmcnt(10)
	v_lshlrev_b32_e32 v123, 16, v21
	v_lshlrev_b32_e32 v102, 16, v21
	v_pk_fma_f32 v[106:107], v[144:145], v[122:123], v[106:107] op_sel:[1,0,0] op_sel_hi:[1,1,1]
	v_pk_fma_f32 v[108:109], v[148:149], v[122:123], v[108:109] op_sel:[0,0,0] op_sel_hi:[0,1,1]
	v_pk_fma_f32 v[110:111], v[150:151], v[122:123], v[60:61] op_sel:[0,0,0] op_sel_hi:[0,1,0]
	s_waitcnt lgkmcnt(9)
	v_lshlrev_b32_e32 v103, 16, v22
	v_lshlrev_b32_e32 v122, 16, v22
	v_pk_fma_f32 v[106:107], v[60:61], v[102:103], v[106:107] op_sel:[1,0,0] op_sel_hi:[1,1,1]
	v_pk_fma_f32 v[108:109], v[146:147], v[102:103], v[108:109] op_sel:[1,0,0] op_sel_hi:[1,1,1]
	v_pk_fma_f32 v[110:111], v[148:149], v[102:103], v[110:111] op_sel:[1,0,0] op_sel_hi:[1,1,1]
	s_waitcnt lgkmcnt(8)
	v_lshlrev_b32_e32 v123, 16, v23
	v_lshlrev_b32_e32 v102, 16, v23
	v_pk_fma_f32 v[106:107], v[146:147], v[122:123], v[106:107] op_sel:[0,0,0] op_sel_hi:[0,1,1]
	v_pk_fma_f32 v[108:109], v[144:145], v[122:123], v[108:109] op_sel:[1,0,0] op_sel_hi:[1,1,1]
	v_pk_fma_f32 v[110:111], v[148:149], v[122:123], v[110:111] op_sel:[0,0,0] op_sel_hi:[0,1,1]
	v_pk_fma_f32 v[112:113], v[150:151], v[122:123], v[60:61] op_sel:[0,0,0] op_sel_hi:[0,1,0]
	ds_read_u16 v16, v89 offset:16384
	ds_read_u16 v17, v89 offset:17408
	ds_read_u16 v18, v89 offset:18432
	ds_read_u16 v19, v89 offset:19456
	ds_read_u16 v20, v89 offset:20480
	ds_read_u16 v21, v89 offset:21504
	ds_read_u16 v22, v89 offset:22528
	ds_read_u16 v23, v89 offset:23552
	s_waitcnt lgkmcnt(15)
	v_lshlrev_b32_e32 v103, 16, v24
	v_lshlrev_b32_e32 v122, 16, v24
	v_pk_fma_f32 v[106:107], v[144:145], v[102:103], v[106:107] op_sel:[0,0,0] op_sel_hi:[0,1,1]
	v_pk_fma_f32 v[108:109], v[60:61], v[102:103], v[108:109] op_sel:[1,0,0] op_sel_hi:[1,1,1]
	v_pk_fma_f32 v[110:111], v[146:147], v[102:103], v[110:111] op_sel:[1,0,0] op_sel_hi:[1,1,1]
	v_pk_fma_f32 v[112:113], v[148:149], v[102:103], v[112:113] op_sel:[1,0,0] op_sel_hi:[1,1,1]
	s_waitcnt lgkmcnt(14)
	v_lshlrev_b32_e32 v123, 16, v25
	v_lshlrev_b32_e32 v102, 16, v25
	v_pk_fma_f32 v[106:107], v[158:159], v[122:123], v[106:107] op_sel:[0,0,0] op_sel_hi:[0,1,1]
	v_pk_fma_f32 v[108:109], v[146:147], v[122:123], v[108:109] op_sel:[0,0,0] op_sel_hi:[0,1,1]
	v_pk_fma_f32 v[110:111], v[144:145], v[122:123], v[110:111] op_sel:[1,0,0] op_sel_hi:[1,1,1]
	v_pk_fma_f32 v[112:113], v[148:149], v[122:123], v[112:113] op_sel:[0,0,0] op_sel_hi:[0,1,1]
	v_pk_fma_f32 v[114:115], v[150:151], v[122:123], v[60:61] op_sel:[0,0,0] op_sel_hi:[0,1,0]
	s_waitcnt lgkmcnt(13)
	v_lshlrev_b32_e32 v103, 16, v26
	v_lshlrev_b32_e32 v122, 16, v26
	v_pk_fma_f32 v[106:107], v[156:157], v[102:103], v[106:107] op_sel:[1,0,0] op_sel_hi:[1,1,1]
	v_pk_fma_f32 v[108:109], v[144:145], v[102:103], v[108:109] op_sel:[0,0,0] op_sel_hi:[0,1,1]
	v_pk_fma_f32 v[110:111], v[60:61], v[102:103], v[110:111] op_sel:[1,0,0] op_sel_hi:[1,1,1]
	v_pk_fma_f32 v[112:113], v[146:147], v[102:103], v[112:113] op_sel:[1,0,0] op_sel_hi:[1,1,1]
	v_pk_fma_f32 v[114:115], v[148:149], v[102:103], v[114:115] op_sel:[1,0,0] op_sel_hi:[1,1,1]
	s_waitcnt lgkmcnt(12)
	v_lshlrev_b32_e32 v123, 16, v27
	v_lshlrev_b32_e32 v102, 16, v27
	v_pk_fma_f32 v[106:107], v[156:157], v[122:123], v[106:107] op_sel:[0,0,0] op_sel_hi:[0,1,1]
	v_pk_fma_f32 v[108:109], v[158:159], v[122:123], v[108:109] op_sel:[0,0,0] op_sel_hi:[0,1,1]
	v_pk_fma_f32 v[110:111], v[146:147], v[122:123], v[110:111] op_sel:[0,0,0] op_sel_hi:[0,1,1]
	v_pk_fma_f32 v[112:113], v[144:145], v[122:123], v[112:113] op_sel:[1,0,0] op_sel_hi:[1,1,1]
	v_pk_fma_f32 v[114:115], v[148:149], v[122:123], v[114:115] op_sel:[0,0,0] op_sel_hi:[0,1,1]
	v_pk_fma_f32 v[116:117], v[150:151], v[122:123], v[60:61] op_sel:[0,0,0] op_sel_hi:[0,1,0]
	s_waitcnt lgkmcnt(11)
	v_lshlrev_b32_e32 v103, 16, v98
	v_lshlrev_b32_e32 v122, 16, v98
	v_pk_fma_f32 v[106:107], v[154:155], v[102:103], v[106:107] op_sel:[1,0,0] op_sel_hi:[1,1,1]
	v_pk_fma_f32 v[108:109], v[156:157], v[102:103], v[108:109] op_sel:[1,0,0] op_sel_hi:[1,1,1]
	v_pk_fma_f32 v[110:111], v[144:145], v[102:103], v[110:111] op_sel:[0,0,0] op_sel_hi:[0,1,1]
	v_pk_fma_f32 v[112:113], v[60:61], v[102:103], v[112:113] op_sel:[1,0,0] op_sel_hi:[1,1,1]
	v_pk_fma_f32 v[114:115], v[146:147], v[102:103], v[114:115] op_sel:[1,0,0] op_sel_hi:[1,1,1]
	v_pk_fma_f32 v[116:117], v[148:149], v[102:103], v[116:117] op_sel:[1,0,0] op_sel_hi:[1,1,1]
	s_waitcnt lgkmcnt(10)
	v_lshlrev_b32_e32 v123, 16, v99
	v_lshlrev_b32_e32 v102, 16, v99
	v_pk_fma_f32 v[106:107], v[152:153], v[122:123], v[106:107] op_sel:[1,0,0] op_sel_hi:[1,1,1]
	v_pk_fma_f32 v[108:109], v[156:157], v[122:123], v[108:109] op_sel:[0,0,0] op_sel_hi:[0,1,1]
	v_pk_fma_f32 v[110:111], v[158:159], v[122:123], v[110:111] op_sel:[0,0,0] op_sel_hi:[0,1,1]
	v_pk_fma_f32 v[112:113], v[146:147], v[122:123], v[112:113] op_sel:[0,0,0] op_sel_hi:[0,1,1]
	v_pk_fma_f32 v[114:115], v[144:145], v[122:123], v[114:115] op_sel:[1,0,0] op_sel_hi:[1,1,1]
	v_pk_fma_f32 v[116:117], v[148:149], v[122:123], v[116:117] op_sel:[0,0,0] op_sel_hi:[0,1,1]
	v_pk_fma_f32 v[118:119], v[150:151], v[122:123], v[60:61] op_sel:[0,0,0] op_sel_hi:[0,1,0]
	s_waitcnt lgkmcnt(9)
	v_lshlrev_b32_e32 v103, 16, v100
	v_lshlrev_b32_e32 v122, 16, v100
	v_pk_fma_f32 v[106:107], v[150:151], v[102:103], v[106:107] op_sel:[1,0,0] op_sel_hi:[1,1,1]
	v_pk_fma_f32 v[108:109], v[154:155], v[102:103], v[108:109] op_sel:[1,0,0] op_sel_hi:[1,1,1]
	v_pk_fma_f32 v[110:111], v[156:157], v[102:103], v[110:111] op_sel:[1,0,0] op_sel_hi:[1,1,1]
	v_pk_fma_f32 v[112:113], v[144:145], v[102:103], v[112:113] op_sel:[0,0,0] op_sel_hi:[0,1,1]
	v_pk_fma_f32 v[114:115], v[60:61], v[102:103], v[114:115] op_sel:[1,0,0] op_sel_hi:[1,1,1]
	v_pk_fma_f32 v[116:117], v[146:147], v[102:103], v[116:117] op_sel:[1,0,0] op_sel_hi:[1,1,1]
	v_pk_fma_f32 v[118:119], v[148:149], v[102:103], v[118:119] op_sel:[1,0,0] op_sel_hi:[1,1,1]
	s_waitcnt lgkmcnt(8)
	v_lshlrev_b32_e32 v123, 16, v101
	v_lshlrev_b32_e32 v102, 16, v101
	v_pk_fma_f32 v[106:107], v[154:155], v[122:123], v[106:107] op_sel:[0,0,0] op_sel_hi:[0,1,1]
	v_pk_fma_f32 v[108:109], v[152:153], v[122:123], v[108:109] op_sel:[1,0,0] op_sel_hi:[1,1,1]
	v_pk_fma_f32 v[110:111], v[156:157], v[122:123], v[110:111] op_sel:[0,0,0] op_sel_hi:[0,1,1]
	v_pk_fma_f32 v[112:113], v[158:159], v[122:123], v[112:113] op_sel:[0,0,0] op_sel_hi:[0,1,1]
	v_pk_fma_f32 v[114:115], v[146:147], v[122:123], v[114:115] op_sel:[0,0,0] op_sel_hi:[0,1,1]
	v_pk_fma_f32 v[116:117], v[144:145], v[122:123], v[116:117] op_sel:[1,0,0] op_sel_hi:[1,1,1]
	v_pk_fma_f32 v[118:119], v[148:149], v[122:123], v[118:119] op_sel:[0,0,0] op_sel_hi:[0,1,1]
	v_pk_fma_f32 v[120:121], v[150:151], v[122:123], v[60:61] op_sel:[0,0,0] op_sel_hi:[0,1,0]
	ds_read_u16 v24, v89 offset:24576
	ds_read_u16 v25, v89 offset:25600
	ds_read_u16 v26, v89 offset:26624
	ds_read_u16 v27, v89 offset:27648
	ds_read_u16 v98, v89 offset:28672
	ds_read_u16 v99, v89 offset:29696
	ds_read_u16 v100, v89 offset:30720
	ds_read_u16 v101, v89 offset:31744
	s_waitcnt lgkmcnt(15)
	v_lshlrev_b32_e32 v103, 16, v16
	v_lshlrev_b32_e32 v122, 16, v16
	v_pk_fma_f32 v[106:107], v[152:153], v[102:103], v[106:107] op_sel:[0,0,0] op_sel_hi:[0,1,1]
	v_pk_fma_f32 v[108:109], v[150:151], v[102:103], v[108:109] op_sel:[1,0,0] op_sel_hi:[1,1,1]
	v_pk_fma_f32 v[110:111], v[154:155], v[102:103], v[110:111] op_sel:[1,0,0] op_sel_hi:[1,1,1]
	v_pk_fma_f32 v[112:113], v[156:157], v[102:103], v[112:113] op_sel:[1,0,0] op_sel_hi:[1,1,1]
	v_pk_fma_f32 v[114:115], v[144:145], v[102:103], v[114:115] op_sel:[0,0,0] op_sel_hi:[0,1,1]
	v_pk_fma_f32 v[116:117], v[60:61], v[102:103], v[116:117] op_sel:[1,0,0] op_sel_hi:[1,1,1]
	v_pk_fma_f32 v[118:119], v[146:147], v[102:103], v[118:119] op_sel:[1,0,0] op_sel_hi:[1,1,1]
	v_pk_fma_f32 v[120:121], v[148:149], v[102:103], v[120:121] op_sel:[1,0,0] op_sel_hi:[1,1,1]
	s_waitcnt lgkmcnt(14)
	v_lshlrev_b32_e32 v123, 16, v17
	v_lshlrev_b32_e32 v102, 16, v17
	v_pk_fma_f32 v[106:107], v[160:161], v[122:123], v[106:107] op_sel:[1,0,0] op_sel_hi:[1,1,1]
	v_pk_fma_f32 v[108:109], v[154:155], v[122:123], v[108:109] op_sel:[0,0,0] op_sel_hi:[0,1,1]
	v_pk_fma_f32 v[110:111], v[152:153], v[122:123], v[110:111] op_sel:[1,0,0] op_sel_hi:[1,1,1]
	v_pk_fma_f32 v[112:113], v[156:157], v[122:123], v[112:113] op_sel:[0,0,0] op_sel_hi:[0,1,1]
	v_pk_fma_f32 v[114:115], v[158:159], v[122:123], v[114:115] op_sel:[0,0,0] op_sel_hi:[0,1,1]
	v_pk_fma_f32 v[116:117], v[146:147], v[122:123], v[116:117] op_sel:[0,0,0] op_sel_hi:[0,1,1]
	v_pk_fma_f32 v[118:119], v[144:145], v[122:123], v[118:119] op_sel:[1,0,0] op_sel_hi:[1,1,1]
	v_pk_fma_f32 v[120:121], v[148:149], v[122:123], v[120:121] op_sel:[0,0,0] op_sel_hi:[0,1,1]
	s_waitcnt lgkmcnt(13)
	v_lshlrev_b32_e32 v103, 16, v18
	v_lshlrev_b32_e32 v122, 16, v18
	v_pk_fma_f32 v[106:107], v[160:161], v[102:103], v[106:107] op_sel:[0,0,0] op_sel_hi:[0,1,1]
	v_pk_fma_f32 v[108:109], v[152:153], v[102:103], v[108:109] op_sel:[0,0,0] op_sel_hi:[0,1,1]
	v_pk_fma_f32 v[110:111], v[150:151], v[102:103], v[110:111] op_sel:[1,0,0] op_sel_hi:[1,1,1]
	v_pk_fma_f32 v[112:113], v[154:155], v[102:103], v[112:113] op_sel:[1,0,0] op_sel_hi:[1,1,1]
	v_pk_fma_f32 v[114:115], v[156:157], v[102:103], v[114:115] op_sel:[1,0,0] op_sel_hi:[1,1,1]
	v_pk_fma_f32 v[116:117], v[144:145], v[102:103], v[116:117] op_sel:[0,0,0] op_sel_hi:[0,1,1]
	v_pk_fma_f32 v[118:119], v[60:61], v[102:103], v[118:119] op_sel:[1,0,0] op_sel_hi:[1,1,1]
	v_pk_fma_f32 v[120:121], v[146:147], v[102:103], v[120:121] op_sel:[1,0,0] op_sel_hi:[1,1,1]
	s_waitcnt lgkmcnt(12)
	v_lshlrev_b32_e32 v123, 16, v19
	v_lshlrev_b32_e32 v102, 16, v19
	v_pk_fma_f32 v[106:107], v[158:159], v[122:123], v[106:107] op_sel:[1,0,0] op_sel_hi:[1,1,1]
	v_pk_fma_f32 v[108:109], v[160:161], v[122:123], v[108:109] op_sel:[1,0,0] op_sel_hi:[1,1,1]
	v_pk_fma_f32 v[110:111], v[154:155], v[122:123], v[110:111] op_sel:[0,0,0] op_sel_hi:[0,1,1]
	v_pk_fma_f32 v[112:113], v[152:153], v[122:123], v[112:113] op_sel:[1,0,0] op_sel_hi:[1,1,1]
	v_pk_fma_f32 v[114:115], v[156:157], v[122:123], v[114:115] op_sel:[0,0,0] op_sel_hi:[0,1,1]
	v_pk_fma_f32 v[116:117], v[158:159], v[122:123], v[116:117] op_sel:[0,0,0] op_sel_hi:[0,1,1]
	v_pk_fma_f32 v[118:119], v[146:147], v[122:123], v[118:119] op_sel:[0,0,0] op_sel_hi:[0,1,1]
	v_pk_fma_f32 v[120:121], v[144:145], v[122:123], v[120:121] op_sel:[1,0,0] op_sel_hi:[1,1,1]
	s_waitcnt lgkmcnt(11)
	v_lshlrev_b32_e32 v103, 16, v20
	v_lshlrev_b32_e32 v122, 16, v20
	v_pk_fma_f32 v[106:107], v[68:69], v[102:103], v[106:107] op_sel:[0,0,0] op_sel_hi:[0,1,1]
	v_pk_fma_f32 v[108:109], v[160:161], v[102:103], v[108:109] op_sel:[0,0,0] op_sel_hi:[0,1,1]
	v_pk_fma_f32 v[110:111], v[152:153], v[102:103], v[110:111] op_sel:[0,0,0] op_sel_hi:[0,1,1]
	v_pk_fma_f32 v[112:113], v[150:151], v[102:103], v[112:113] op_sel:[1,0,0] op_sel_hi:[1,1,1]
	v_pk_fma_f32 v[114:115], v[154:155], v[102:103], v[114:115] op_sel:[1,0,0] op_sel_hi:[1,1,1]
	v_pk_fma_f32 v[116:117], v[156:157], v[102:103], v[116:117] op_sel:[1,0,0] op_sel_hi:[1,1,1]
	v_pk_fma_f32 v[118:119], v[144:145], v[102:103], v[118:119] op_sel:[0,0,0] op_sel_hi:[0,1,1]
	v_pk_fma_f32 v[120:121], v[60:61], v[102:103], v[120:121] op_sel:[1,0,0] op_sel_hi:[1,1,1]
	s_waitcnt lgkmcnt(10)
	v_lshlrev_b32_e32 v123, 16, v21
	v_lshlrev_b32_e32 v102, 16, v21
	v_pk_fma_f32 v[106:107], v[68:69], v[122:123], v[106:107] op_sel:[1,0,0] op_sel_hi:[1,1,1]
	v_pk_fma_f32 v[108:109], v[158:159], v[122:123], v[108:109] op_sel:[1,0,0] op_sel_hi:[1,1,1]
	v_pk_fma_f32 v[110:111], v[160:161], v[122:123], v[110:111] op_sel:[1,0,0] op_sel_hi:[1,1,1]
	v_pk_fma_f32 v[112:113], v[154:155], v[122:123], v[112:113] op_sel:[0,0,0] op_sel_hi:[0,1,1]
	v_pk_fma_f32 v[114:115], v[152:153], v[122:123], v[114:115] op_sel:[1,0,0] op_sel_hi:[1,1,1]
	v_pk_fma_f32 v[116:117], v[156:157], v[122:123], v[116:117] op_sel:[0,0,0] op_sel_hi:[0,1,1]
	v_pk_fma_f32 v[118:119], v[158:159], v[122:123], v[118:119] op_sel:[0,0,0] op_sel_hi:[0,1,1]
	v_pk_fma_f32 v[120:121], v[146:147], v[122:123], v[120:121] op_sel:[0,0,0] op_sel_hi:[0,1,1]
	s_waitcnt lgkmcnt(9)
	v_lshlrev_b32_e32 v103, 16, v22
	v_lshlrev_b32_e32 v122, 16, v22
	v_pk_fma_f32 v[106:107], v[62:63], v[102:103], v[106:107] op_sel:[0,0,0] op_sel_hi:[0,1,1]
	v_pk_fma_f32 v[108:109], v[68:69], v[102:103], v[108:109] op_sel:[0,0,0] op_sel_hi:[0,1,1]
	v_pk_fma_f32 v[110:111], v[160:161], v[102:103], v[110:111] op_sel:[0,0,0] op_sel_hi:[0,1,1]
	v_pk_fma_f32 v[112:113], v[152:153], v[102:103], v[112:113] op_sel:[0,0,0] op_sel_hi:[0,1,1]
	v_pk_fma_f32 v[114:115], v[150:151], v[102:103], v[114:115] op_sel:[1,0,0] op_sel_hi:[1,1,1]
	v_pk_fma_f32 v[116:117], v[154:155], v[102:103], v[116:117] op_sel:[1,0,0] op_sel_hi:[1,1,1]
	v_pk_fma_f32 v[118:119], v[156:157], v[102:103], v[118:119] op_sel:[1,0,0] op_sel_hi:[1,1,1]
	v_pk_fma_f32 v[120:121], v[144:145], v[102:103], v[120:121] op_sel:[0,0,0] op_sel_hi:[0,1,1]
	s_waitcnt lgkmcnt(8)
	v_lshlrev_b32_e32 v123, 16, v23
	v_lshlrev_b32_e32 v102, 16, v23
	v_pk_fma_f32 v[106:107], v[62:63], v[122:123], v[106:107] op_sel:[1,0,0] op_sel_hi:[1,1,1]
	v_pk_fma_f32 v[108:109], v[68:69], v[122:123], v[108:109] op_sel:[1,0,0] op_sel_hi:[1,1,1]
	v_pk_fma_f32 v[110:111], v[158:159], v[122:123], v[110:111] op_sel:[1,0,0] op_sel_hi:[1,1,1]
	v_pk_fma_f32 v[112:113], v[160:161], v[122:123], v[112:113] op_sel:[1,0,0] op_sel_hi:[1,1,1]
	v_pk_fma_f32 v[114:115], v[154:155], v[122:123], v[114:115] op_sel:[0,0,0] op_sel_hi:[0,1,1]
	v_pk_fma_f32 v[116:117], v[152:153], v[122:123], v[116:117] op_sel:[1,0,0] op_sel_hi:[1,1,1]
	v_pk_fma_f32 v[118:119], v[156:157], v[122:123], v[118:119] op_sel:[0,0,0] op_sel_hi:[0,1,1]
	v_pk_fma_f32 v[120:121], v[158:159], v[122:123], v[120:121] op_sel:[0,0,0] op_sel_hi:[0,1,1]
	ds_read_u16 v16, v89 offset:32768
	ds_read_u16 v17, v89 offset:33792
	ds_read_u16 v18, v89 offset:34816
	ds_read_u16 v19, v89 offset:35840
	ds_read_u16 v20, v89 offset:36864
	ds_read_u16 v21, v89 offset:37888
	ds_read_u16 v22, v89 offset:38912
	ds_read_u16 v23, v89 offset:39936
	s_waitcnt lgkmcnt(15)
	v_lshlrev_b32_e32 v103, 16, v24
	v_lshlrev_b32_e32 v122, 16, v24
	v_pk_fma_f32 v[106:107], v[66:67], v[102:103], v[106:107] op_sel:[0,0,0] op_sel_hi:[0,1,1]
	v_pk_fma_f32 v[108:109], v[62:63], v[102:103], v[108:109] op_sel:[0,0,0] op_sel_hi:[0,1,1]
	v_pk_fma_f32 v[110:111], v[68:69], v[102:103], v[110:111] op_sel:[0,0,0] op_sel_hi:[0,1,1]
	v_pk_fma_f32 v[112:113], v[160:161], v[102:103], v[112:113] op_sel:[0,0,0] op_sel_hi:[0,1,1]
	v_pk_fma_f32 v[114:115], v[152:153], v[102:103], v[114:115] op_sel:[0,0,0] op_sel_hi:[0,1,1]
	v_pk_fma_f32 v[116:117], v[150:151], v[102:103], v[116:117] op_sel:[1,0,0] op_sel_hi:[1,1,1]
	v_pk_fma_f32 v[118:119], v[154:155], v[102:103], v[118:119] op_sel:[1,0,0] op_sel_hi:[1,1,1]
	v_pk_fma_f32 v[120:121], v[156:157], v[102:103], v[120:121] op_sel:[1,0,0] op_sel_hi:[1,1,1]
	s_waitcnt lgkmcnt(14)
	v_lshlrev_b32_e32 v123, 16, v25
	v_lshlrev_b32_e32 v102, 16, v25
	v_pk_fma_f32 v[106:107], v[66:67], v[122:123], v[106:107] op_sel:[1,0,0] op_sel_hi:[1,1,1]
	v_pk_fma_f32 v[108:109], v[62:63], v[122:123], v[108:109] op_sel:[1,0,0] op_sel_hi:[1,1,1]
	v_pk_fma_f32 v[110:111], v[68:69], v[122:123], v[110:111] op_sel:[1,0,0] op_sel_hi:[1,1,1]
	v_pk_fma_f32 v[112:113], v[158:159], v[122:123], v[112:113] op_sel:[1,0,0] op_sel_hi:[1,1,1]
	v_pk_fma_f32 v[114:115], v[160:161], v[122:123], v[114:115] op_sel:[1,0,0] op_sel_hi:[1,1,1]
	v_pk_fma_f32 v[116:117], v[154:155], v[122:123], v[116:117] op_sel:[0,0,0] op_sel_hi:[0,1,1]
	v_pk_fma_f32 v[118:119], v[152:153], v[122:123], v[118:119] op_sel:[1,0,0] op_sel_hi:[1,1,1]
	v_pk_fma_f32 v[120:121], v[156:157], v[122:123], v[120:121] op_sel:[0,0,0] op_sel_hi:[0,1,1]
	s_waitcnt lgkmcnt(13)
	v_lshlrev_b32_e32 v103, 16, v26
	v_lshlrev_b32_e32 v122, 16, v26
	v_pk_fma_f32 v[106:107], v[74:75], v[102:103], v[106:107] op_sel:[0,0,0] op_sel_hi:[0,1,1]
	v_pk_fma_f32 v[108:109], v[66:67], v[102:103], v[108:109] op_sel:[0,0,0] op_sel_hi:[0,1,1]
	v_pk_fma_f32 v[110:111], v[62:63], v[102:103], v[110:111] op_sel:[0,0,0] op_sel_hi:[0,1,1]
	v_pk_fma_f32 v[112:113], v[68:69], v[102:103], v[112:113] op_sel:[0,0,0] op_sel_hi:[0,1,1]
	v_pk_fma_f32 v[114:115], v[160:161], v[102:103], v[114:115] op_sel:[0,0,0] op_sel_hi:[0,1,1]
	v_pk_fma_f32 v[116:117], v[152:153], v[102:103], v[116:117] op_sel:[0,0,0] op_sel_hi:[0,1,1]
	v_pk_fma_f32 v[118:119], v[150:151], v[102:103], v[118:119] op_sel:[1,0,0] op_sel_hi:[1,1,1]
	v_pk_fma_f32 v[120:121], v[154:155], v[102:103], v[120:121] op_sel:[1,0,0] op_sel_hi:[1,1,1]
	s_waitcnt lgkmcnt(12)
	v_lshlrev_b32_e32 v123, 16, v27
	v_lshlrev_b32_e32 v102, 16, v27
	v_pk_fma_f32 v[106:107], v[74:75], v[122:123], v[106:107] op_sel:[1,0,0] op_sel_hi:[1,1,1]
	v_pk_fma_f32 v[108:109], v[66:67], v[122:123], v[108:109] op_sel:[1,0,0] op_sel_hi:[1,1,1]
	v_pk_fma_f32 v[110:111], v[62:63], v[122:123], v[110:111] op_sel:[1,0,0] op_sel_hi:[1,1,1]
	v_pk_fma_f32 v[112:113], v[68:69], v[122:123], v[112:113] op_sel:[1,0,0] op_sel_hi:[1,1,1]
	v_pk_fma_f32 v[114:115], v[158:159], v[122:123], v[114:115] op_sel:[1,0,0] op_sel_hi:[1,1,1]
	v_pk_fma_f32 v[116:117], v[160:161], v[122:123], v[116:117] op_sel:[1,0,0] op_sel_hi:[1,1,1]
	v_pk_fma_f32 v[118:119], v[154:155], v[122:123], v[118:119] op_sel:[0,0,0] op_sel_hi:[0,1,1]
	v_pk_fma_f32 v[120:121], v[152:153], v[122:123], v[120:121] op_sel:[1,0,0] op_sel_hi:[1,1,1]
	s_waitcnt lgkmcnt(11)
	v_lshlrev_b32_e32 v103, 16, v98
	v_lshlrev_b32_e32 v122, 16, v98
	v_pk_fma_f32 v[106:107], v[72:73], v[102:103], v[106:107] op_sel:[0,0,0] op_sel_hi:[0,1,1]
	v_pk_fma_f32 v[108:109], v[74:75], v[102:103], v[108:109] op_sel:[0,0,0] op_sel_hi:[0,1,1]
	v_pk_fma_f32 v[110:111], v[66:67], v[102:103], v[110:111] op_sel:[0,0,0] op_sel_hi:[0,1,1]
	v_pk_fma_f32 v[112:113], v[62:63], v[102:103], v[112:113] op_sel:[0,0,0] op_sel_hi:[0,1,1]
	v_pk_fma_f32 v[114:115], v[68:69], v[102:103], v[114:115] op_sel:[0,0,0] op_sel_hi:[0,1,1]
	v_pk_fma_f32 v[116:117], v[160:161], v[102:103], v[116:117] op_sel:[0,0,0] op_sel_hi:[0,1,1]
	v_pk_fma_f32 v[118:119], v[152:153], v[102:103], v[118:119] op_sel:[0,0,0] op_sel_hi:[0,1,1]
	v_pk_fma_f32 v[120:121], v[150:151], v[102:103], v[120:121] op_sel:[1,0,0] op_sel_hi:[1,1,1]
	s_waitcnt lgkmcnt(10)
	v_lshlrev_b32_e32 v123, 16, v99
	v_lshlrev_b32_e32 v102, 16, v99
	v_pk_fma_f32 v[106:107], v[72:73], v[122:123], v[106:107] op_sel:[1,0,0] op_sel_hi:[1,1,1]
	v_pk_fma_f32 v[108:109], v[74:75], v[122:123], v[108:109] op_sel:[1,0,0] op_sel_hi:[1,1,1]
	v_pk_fma_f32 v[110:111], v[66:67], v[122:123], v[110:111] op_sel:[1,0,0] op_sel_hi:[1,1,1]
	v_pk_fma_f32 v[112:113], v[62:63], v[122:123], v[112:113] op_sel:[1,0,0] op_sel_hi:[1,1,1]
	v_pk_fma_f32 v[114:115], v[68:69], v[122:123], v[114:115] op_sel:[1,0,0] op_sel_hi:[1,1,1]
	v_pk_fma_f32 v[116:117], v[158:159], v[122:123], v[116:117] op_sel:[1,0,0] op_sel_hi:[1,1,1]
	v_pk_fma_f32 v[118:119], v[160:161], v[122:123], v[118:119] op_sel:[1,0,0] op_sel_hi:[1,1,1]
	v_pk_fma_f32 v[120:121], v[154:155], v[122:123], v[120:121] op_sel:[0,0,0] op_sel_hi:[0,1,1]
	s_waitcnt lgkmcnt(9)
	v_lshlrev_b32_e32 v103, 16, v100
	v_lshlrev_b32_e32 v122, 16, v100
	v_pk_fma_f32 v[106:107], v[70:71], v[102:103], v[106:107] op_sel:[0,0,0] op_sel_hi:[0,1,1]
	v_pk_fma_f32 v[108:109], v[72:73], v[102:103], v[108:109] op_sel:[0,0,0] op_sel_hi:[0,1,1]
	v_pk_fma_f32 v[110:111], v[74:75], v[102:103], v[110:111] op_sel:[0,0,0] op_sel_hi:[0,1,1]
	v_pk_fma_f32 v[112:113], v[66:67], v[102:103], v[112:113] op_sel:[0,0,0] op_sel_hi:[0,1,1]
	v_pk_fma_f32 v[114:115], v[62:63], v[102:103], v[114:115] op_sel:[0,0,0] op_sel_hi:[0,1,1]
	v_pk_fma_f32 v[116:117], v[68:69], v[102:103], v[116:117] op_sel:[0,0,0] op_sel_hi:[0,1,1]
	v_pk_fma_f32 v[118:119], v[160:161], v[102:103], v[118:119] op_sel:[0,0,0] op_sel_hi:[0,1,1]
	v_pk_fma_f32 v[120:121], v[152:153], v[102:103], v[120:121] op_sel:[0,0,0] op_sel_hi:[0,1,1]
	s_waitcnt lgkmcnt(8)
	v_lshlrev_b32_e32 v123, 16, v101
	v_lshlrev_b32_e32 v102, 16, v101
	v_pk_fma_f32 v[106:107], v[70:71], v[122:123], v[106:107] op_sel:[1,0,0] op_sel_hi:[1,1,1]
	v_pk_fma_f32 v[108:109], v[72:73], v[122:123], v[108:109] op_sel:[1,0,0] op_sel_hi:[1,1,1]
	v_pk_fma_f32 v[110:111], v[74:75], v[122:123], v[110:111] op_sel:[1,0,0] op_sel_hi:[1,1,1]
	v_pk_fma_f32 v[112:113], v[66:67], v[122:123], v[112:113] op_sel:[1,0,0] op_sel_hi:[1,1,1]
	v_pk_fma_f32 v[114:115], v[62:63], v[122:123], v[114:115] op_sel:[1,0,0] op_sel_hi:[1,1,1]
	v_pk_fma_f32 v[116:117], v[68:69], v[122:123], v[116:117] op_sel:[1,0,0] op_sel_hi:[1,1,1]
	v_pk_fma_f32 v[118:119], v[158:159], v[122:123], v[118:119] op_sel:[1,0,0] op_sel_hi:[1,1,1]
	v_pk_fma_f32 v[120:121], v[160:161], v[122:123], v[120:121] op_sel:[1,0,0] op_sel_hi:[1,1,1]
	ds_read_u16 v24, v89 offset:40960
	ds_read_u16 v25, v89 offset:41984
	ds_read_u16 v26, v89 offset:43008
	ds_read_u16 v27, v89 offset:44032
	ds_read_u16 v98, v89 offset:45056
	ds_read_u16 v99, v89 offset:46080
	s_waitcnt lgkmcnt(13)
	v_lshlrev_b32_e32 v103, 16, v16
	v_lshlrev_b32_e32 v122, 16, v16
	v_pk_fma_f32 v[108:109], v[70:71], v[102:103], v[108:109] op_sel:[0,0,0] op_sel_hi:[0,1,1]
	v_pk_fma_f32 v[110:111], v[72:73], v[102:103], v[110:111] op_sel:[0,0,0] op_sel_hi:[0,1,1]
	v_pk_fma_f32 v[112:113], v[74:75], v[102:103], v[112:113] op_sel:[0,0,0] op_sel_hi:[0,1,1]
	v_pk_fma_f32 v[114:115], v[66:67], v[102:103], v[114:115] op_sel:[0,0,0] op_sel_hi:[0,1,1]
	v_pk_fma_f32 v[116:117], v[62:63], v[102:103], v[116:117] op_sel:[0,0,0] op_sel_hi:[0,1,1]
	v_pk_fma_f32 v[118:119], v[68:69], v[102:103], v[118:119] op_sel:[0,0,0] op_sel_hi:[0,1,1]
	v_pk_fma_f32 v[120:121], v[160:161], v[102:103], v[120:121] op_sel:[0,0,0] op_sel_hi:[0,1,1]
	s_waitcnt lgkmcnt(12)
	v_lshlrev_b32_e32 v123, 16, v17
	v_lshlrev_b32_e32 v102, 16, v17
	v_pk_fma_f32 v[108:109], v[70:71], v[122:123], v[108:109] op_sel:[1,0,0] op_sel_hi:[1,1,1]
	v_pk_fma_f32 v[110:111], v[72:73], v[122:123], v[110:111] op_sel:[1,0,0] op_sel_hi:[1,1,1]
	v_pk_fma_f32 v[112:113], v[74:75], v[122:123], v[112:113] op_sel:[1,0,0] op_sel_hi:[1,1,1]
	v_pk_fma_f32 v[114:115], v[66:67], v[122:123], v[114:115] op_sel:[1,0,0] op_sel_hi:[1,1,1]
	v_pk_fma_f32 v[116:117], v[62:63], v[122:123], v[116:117] op_sel:[1,0,0] op_sel_hi:[1,1,1]
	v_pk_fma_f32 v[118:119], v[68:69], v[122:123], v[118:119] op_sel:[1,0,0] op_sel_hi:[1,1,1]
	v_pk_fma_f32 v[120:121], v[158:159], v[122:123], v[120:121] op_sel:[1,0,0] op_sel_hi:[1,1,1]
	s_waitcnt lgkmcnt(11)
	v_lshlrev_b32_e32 v103, 16, v18
	v_lshlrev_b32_e32 v122, 16, v18
	v_pk_fma_f32 v[110:111], v[70:71], v[102:103], v[110:111] op_sel:[0,0,0] op_sel_hi:[0,1,1]
	v_pk_fma_f32 v[112:113], v[72:73], v[102:103], v[112:113] op_sel:[0,0,0] op_sel_hi:[0,1,1]
	v_pk_fma_f32 v[114:115], v[74:75], v[102:103], v[114:115] op_sel:[0,0,0] op_sel_hi:[0,1,1]
	v_pk_fma_f32 v[116:117], v[66:67], v[102:103], v[116:117] op_sel:[0,0,0] op_sel_hi:[0,1,1]
	v_pk_fma_f32 v[118:119], v[62:63], v[102:103], v[118:119] op_sel:[0,0,0] op_sel_hi:[0,1,1]
	v_pk_fma_f32 v[120:121], v[68:69], v[102:103], v[120:121] op_sel:[0,0,0] op_sel_hi:[0,1,1]
	s_waitcnt lgkmcnt(10)
	v_lshlrev_b32_e32 v123, 16, v19
	v_lshlrev_b32_e32 v102, 16, v19
	v_pk_fma_f32 v[110:111], v[70:71], v[122:123], v[110:111] op_sel:[1,0,0] op_sel_hi:[1,1,1]
	v_pk_fma_f32 v[112:113], v[72:73], v[122:123], v[112:113] op_sel:[1,0,0] op_sel_hi:[1,1,1]
	v_pk_fma_f32 v[114:115], v[74:75], v[122:123], v[114:115] op_sel:[1,0,0] op_sel_hi:[1,1,1]
	v_pk_fma_f32 v[116:117], v[66:67], v[122:123], v[116:117] op_sel:[1,0,0] op_sel_hi:[1,1,1]
	v_pk_fma_f32 v[118:119], v[62:63], v[122:123], v[118:119] op_sel:[1,0,0] op_sel_hi:[1,1,1]
	v_pk_fma_f32 v[120:121], v[68:69], v[122:123], v[120:121] op_sel:[1,0,0] op_sel_hi:[1,1,1]
	s_waitcnt lgkmcnt(9)
	v_lshlrev_b32_e32 v103, 16, v20
	v_lshlrev_b32_e32 v122, 16, v20
	v_pk_fma_f32 v[112:113], v[70:71], v[102:103], v[112:113] op_sel:[0,0,0] op_sel_hi:[0,1,1]
	v_pk_fma_f32 v[114:115], v[72:73], v[102:103], v[114:115] op_sel:[0,0,0] op_sel_hi:[0,1,1]
	v_pk_fma_f32 v[116:117], v[74:75], v[102:103], v[116:117] op_sel:[0,0,0] op_sel_hi:[0,1,1]
	v_pk_fma_f32 v[118:119], v[66:67], v[102:103], v[118:119] op_sel:[0,0,0] op_sel_hi:[0,1,1]
	v_pk_fma_f32 v[120:121], v[62:63], v[102:103], v[120:121] op_sel:[0,0,0] op_sel_hi:[0,1,1]
	s_waitcnt lgkmcnt(8)
	v_lshlrev_b32_e32 v123, 16, v21
	v_lshlrev_b32_e32 v102, 16, v21
	v_pk_fma_f32 v[112:113], v[70:71], v[122:123], v[112:113] op_sel:[1,0,0] op_sel_hi:[1,1,1]
	v_pk_fma_f32 v[114:115], v[72:73], v[122:123], v[114:115] op_sel:[1,0,0] op_sel_hi:[1,1,1]
	v_pk_fma_f32 v[116:117], v[74:75], v[122:123], v[116:117] op_sel:[1,0,0] op_sel_hi:[1,1,1]
	v_pk_fma_f32 v[118:119], v[66:67], v[122:123], v[118:119] op_sel:[1,0,0] op_sel_hi:[1,1,1]
	v_pk_fma_f32 v[120:121], v[62:63], v[122:123], v[120:121] op_sel:[1,0,0] op_sel_hi:[1,1,1]
	s_waitcnt lgkmcnt(7)
	v_lshlrev_b32_e32 v103, 16, v22
	v_lshlrev_b32_e32 v122, 16, v22
	v_pk_fma_f32 v[114:115], v[70:71], v[102:103], v[114:115] op_sel:[0,0,0] op_sel_hi:[0,1,1]
	v_pk_fma_f32 v[116:117], v[72:73], v[102:103], v[116:117] op_sel:[0,0,0] op_sel_hi:[0,1,1]
	v_pk_fma_f32 v[118:119], v[74:75], v[102:103], v[118:119] op_sel:[0,0,0] op_sel_hi:[0,1,1]
	v_pk_fma_f32 v[120:121], v[66:67], v[102:103], v[120:121] op_sel:[0,0,0] op_sel_hi:[0,1,1]
	s_waitcnt lgkmcnt(6)
	v_lshlrev_b32_e32 v123, 16, v23
	v_lshlrev_b32_e32 v102, 16, v23
	v_pk_fma_f32 v[114:115], v[70:71], v[122:123], v[114:115] op_sel:[1,0,0] op_sel_hi:[1,1,1]
	v_pk_fma_f32 v[116:117], v[72:73], v[122:123], v[116:117] op_sel:[1,0,0] op_sel_hi:[1,1,1]
	v_pk_fma_f32 v[118:119], v[74:75], v[122:123], v[118:119] op_sel:[1,0,0] op_sel_hi:[1,1,1]
	v_pk_fma_f32 v[120:121], v[66:67], v[122:123], v[120:121] op_sel:[1,0,0] op_sel_hi:[1,1,1]
	s_waitcnt lgkmcnt(5)
	v_lshlrev_b32_e32 v103, 16, v24
	v_lshlrev_b32_e32 v122, 16, v24
	v_pk_fma_f32 v[116:117], v[70:71], v[102:103], v[116:117] op_sel:[0,0,0] op_sel_hi:[0,1,1]
	v_pk_fma_f32 v[118:119], v[72:73], v[102:103], v[118:119] op_sel:[0,0,0] op_sel_hi:[0,1,1]
	v_pk_fma_f32 v[120:121], v[74:75], v[102:103], v[120:121] op_sel:[0,0,0] op_sel_hi:[0,1,1]
	s_waitcnt lgkmcnt(4)
	v_lshlrev_b32_e32 v123, 16, v25
	v_lshlrev_b32_e32 v102, 16, v25
	v_pk_fma_f32 v[116:117], v[70:71], v[122:123], v[116:117] op_sel:[1,0,0] op_sel_hi:[1,1,1]
	v_pk_fma_f32 v[118:119], v[72:73], v[122:123], v[118:119] op_sel:[1,0,0] op_sel_hi:[1,1,1]
	v_pk_fma_f32 v[120:121], v[74:75], v[122:123], v[120:121] op_sel:[1,0,0] op_sel_hi:[1,1,1]
	s_waitcnt lgkmcnt(3)
	v_lshlrev_b32_e32 v103, 16, v26
	v_lshlrev_b32_e32 v122, 16, v26
	v_pk_fma_f32 v[118:119], v[70:71], v[102:103], v[118:119] op_sel:[0,0,0] op_sel_hi:[0,1,1]
	v_pk_fma_f32 v[120:121], v[72:73], v[102:103], v[120:121] op_sel:[0,0,0] op_sel_hi:[0,1,1]
	s_waitcnt lgkmcnt(2)
	v_lshlrev_b32_e32 v123, 16, v27
	v_lshlrev_b32_e32 v102, 16, v27
	v_pk_fma_f32 v[118:119], v[70:71], v[122:123], v[118:119] op_sel:[1,0,0] op_sel_hi:[1,1,1]
	v_pk_fma_f32 v[120:121], v[72:73], v[122:123], v[120:121] op_sel:[1,0,0] op_sel_hi:[1,1,1]
	s_waitcnt lgkmcnt(1)
	v_lshlrev_b32_e32 v103, 16, v98
	v_lshlrev_b32_e32 v122, 16, v98
	v_pk_fma_f32 v[120:121], v[70:71], v[102:103], v[120:121] op_sel:[0,0,0] op_sel_hi:[0,1,1]
	s_waitcnt lgkmcnt(0)
	v_lshlrev_b32_e32 v123, 16, v99
	s_nop 0
	v_pk_fma_f32 v[120:121], v[70:71], v[122:123], v[120:121] op_sel:[1,0,0] op_sel_hi:[1,1,1]
	s_nop 0
	v_mov_b32_e32 v49, v106
	v_mov_b32_e32 v47, v107
	v_mov_b32_e32 v45, v108
	v_mov_b32_e32 v43, v109
	v_mov_b32_e32 v27, v110
	v_mov_b32_e32 v26, v111
	v_mov_b32_e32 v25, v112
	v_mov_b32_e32 v23, v113
	v_mov_b32_e32 v24, v114
	v_mov_b32_e32 v22, v115
	v_mov_b32_e32 v21, v116
	v_mov_b32_e32 v20, v117
	v_mov_b32_e32 v19, v118
	v_mov_b32_e32 v18, v119
	v_mov_b32_e32 v17, v120
	v_mov_b32_e32 v16, v121
	v_cmp_lt_i32_e32 vcc, v224, v218
	s_nop 0
	v_cndmask_b32_e64 v114, v49, v24, s[26:27]
	v_cndmask_b32_e32 v98, v217, v224, vcc
	v_lshlrev_b32_e32 v98, 2, v98
	ds_bpermute_b32 v114, v98, v114
	v_mul_f32_e32 v99, v49, v49
	v_mul_f32_e32 v109, v24, v24
	v_cndmask_b32_e64 v118, v24, v49, s[26:27]
	v_mul_f32_e32 v100, v47, v47
	s_waitcnt lgkmcnt(0)
	v_add_f32_e32 v114, v118, v114
	v_cndmask_b32_e64 v118, v99, v109, s[26:27]
	v_mul_f32_e32 v110, v22, v22
	v_cndmask_b32_e64 v99, v109, v99, s[26:27]
	ds_bpermute_b32 v109, v98, v118
	v_cndmask_b32_e64 v118, v47, v22, s[26:27]
	ds_bpermute_b32 v118, v98, v118
	v_cndmask_b32_e64 v119, v100, v110, s[26:27]
	ds_bpermute_b32 v119, v98, v119
	s_waitcnt lgkmcnt(2)
	v_add_f32_e32 v109, v99, v109
	v_cndmask_b32_e64 v99, v22, v47, s[26:27]
	s_waitcnt lgkmcnt(1)
	v_add_f32_e32 v118, v99, v118
	v_cndmask_b32_e64 v99, v110, v100, s[26:27]
	v_mul_f32_e32 v101, v45, v45
	v_mul_f32_e32 v111, v21, v21
	s_waitcnt lgkmcnt(0)
	v_add_f32_e32 v100, v99, v119
	v_cndmask_b32_e64 v99, v45, v21, s[26:27]
	ds_bpermute_b32 v99, v98, v99
	v_cndmask_b32_e64 v119, v101, v111, s[26:27]
	ds_bpermute_b32 v119, v98, v119
	v_cndmask_b32_e64 v120, v43, v20, s[26:27]
	ds_bpermute_b32 v120, v98, v120
	v_cndmask_b32_e64 v110, v21, v45, s[26:27]
	s_waitcnt lgkmcnt(2)
	v_add_f32_e32 v110, v110, v99
	v_cndmask_b32_e64 v99, v111, v101, s[26:27]
	v_mul_f32_e32 v102, v43, v43
	v_mul_f32_e32 v112, v20, v20
	s_waitcnt lgkmcnt(1)
	v_add_f32_e32 v101, v99, v119
	v_cndmask_b32_e64 v99, v20, v43, s[26:27]
	s_waitcnt lgkmcnt(0)
	v_add_f32_e32 v111, v99, v120
	v_cndmask_b32_e64 v99, v102, v112, s[26:27]
	v_mul_f32_e32 v103, v27, v27
	v_mul_f32_e32 v113, v19, v19
	v_cndmask_b32_e64 v102, v112, v102, s[26:27]
	ds_bpermute_b32 v99, v98, v99
	v_cndmask_b32_e64 v112, v27, v19, s[26:27]
	ds_bpermute_b32 v112, v98, v112
	v_cndmask_b32_e64 v119, v103, v113, s[26:27]
	ds_bpermute_b32 v119, v98, v119
	s_waitcnt lgkmcnt(2)
	v_add_f32_e32 v102, v102, v99
	v_cndmask_b32_e64 v99, v19, v27, s[26:27]
	s_waitcnt lgkmcnt(1)
	v_add_f32_e32 v112, v99, v112
	v_cndmask_b32_e64 v99, v113, v103, s[26:27]
	v_mul_f32_e32 v106, v26, v26
	v_mul_f32_e32 v115, v18, v18
	s_waitcnt lgkmcnt(0)
	v_add_f32_e32 v103, v99, v119
	v_cndmask_b32_e64 v99, v26, v18, s[26:27]
	ds_bpermute_b32 v99, v98, v99
	v_cndmask_b32_e64 v119, v106, v115, s[26:27]
	ds_bpermute_b32 v119, v98, v119
	v_cndmask_b32_e64 v120, v25, v17, s[26:27]
	ds_bpermute_b32 v120, v98, v120
	v_cndmask_b32_e64 v113, v18, v26, s[26:27]
	s_waitcnt lgkmcnt(2)
	v_add_f32_e32 v113, v113, v99
	v_cndmask_b32_e64 v99, v115, v106, s[26:27]
	v_mul_f32_e32 v107, v25, v25
	v_mul_f32_e32 v116, v17, v17
	s_waitcnt lgkmcnt(1)
	v_add_f32_e32 v106, v99, v119
	v_cndmask_b32_e64 v99, v17, v25, s[26:27]
	s_waitcnt lgkmcnt(0)
	v_add_f32_e32 v115, v99, v120
	v_cndmask_b32_e64 v99, v107, v116, s[26:27]
	v_mul_f32_e32 v108, v23, v23
	v_mul_f32_e32 v117, v16, v16
	v_cndmask_b32_e64 v107, v116, v107, s[26:27]
	ds_bpermute_b32 v99, v98, v99
	v_cndmask_b32_e64 v116, v23, v16, s[26:27]
	ds_bpermute_b32 v116, v98, v116
	v_cndmask_b32_e64 v119, v108, v117, s[26:27]
	ds_bpermute_b32 v119, v98, v119
	s_waitcnt lgkmcnt(2)
	v_add_f32_e32 v107, v107, v99
	v_cndmask_b32_e64 v99, v16, v23, s[26:27]
	s_waitcnt lgkmcnt(1)
	v_add_f32_e32 v116, v99, v116
	v_cndmask_b32_e64 v99, v117, v108, s[26:27]
	v_cmp_lt_i32_e32 vcc, v223, v218
	s_waitcnt lgkmcnt(0)
	v_add_f32_e32 v108, v99, v119
	v_cndmask_b32_e64 v117, v114, v112, s[4:5]
	v_cndmask_b32_e32 v99, v217, v223, vcc
	v_lshlrev_b32_e32 v99, 2, v99
	v_cndmask_b32_e64 v112, v112, v114, s[4:5]
	ds_bpermute_b32 v114, v99, v117
	v_cndmask_b32_e64 v117, v109, v103, s[4:5]
	v_cndmask_b32_e64 v119, v118, v113, s[4:5]
	v_cndmask_b32_e64 v103, v103, v109, s[4:5]
	v_cndmask_b32_e64 v109, v113, v118, s[4:5]
	v_cndmask_b32_e64 v113, v100, v106, s[4:5]
	v_cndmask_b32_e64 v100, v106, v100, s[4:5]
	ds_bpermute_b32 v106, v99, v113
	v_cndmask_b32_e64 v113, v110, v115, s[4:5]
	s_waitcnt lgkmcnt(1)
	v_add_f32_e32 v112, v112, v114
	ds_bpermute_b32 v113, v99, v113
	v_cndmask_b32_e64 v114, v101, v107, s[4:5]
	ds_bpermute_b32 v114, v99, v114
	s_waitcnt lgkmcnt(2)
	v_add_f32_e32 v106, v100, v106
	v_cndmask_b32_e64 v100, v115, v110, s[4:5]
	s_waitcnt lgkmcnt(1)
	v_add_f32_e32 v110, v100, v113
	v_cndmask_b32_e64 v100, v107, v101, s[4:5]
	ds_bpermute_b32 v117, v99, v117
	s_waitcnt lgkmcnt(1)
	v_add_f32_e32 v101, v100, v114
	v_cndmask_b32_e64 v100, v111, v116, s[4:5]
	ds_bpermute_b32 v119, v99, v119
	v_cndmask_b32_e64 v107, v116, v111, s[4:5]
	ds_bpermute_b32 v111, v99, v100
	v_cndmask_b32_e64 v100, v102, v108, s[4:5]
	ds_bpermute_b32 v113, v99, v100
	v_cmp_lt_i32_e32 vcc, v222, v218
	s_waitcnt lgkmcnt(3)
	v_add_f32_e32 v103, v103, v117
	s_waitcnt lgkmcnt(2)
	v_add_f32_e32 v109, v109, v119
	v_cndmask_b32_e32 v100, v217, v222, vcc
	v_lshlrev_b32_e32 v100, 2, v100
	v_cndmask_b32_e64 v114, v112, v110, s[6:7]
	s_waitcnt lgkmcnt(1)
	v_add_f32_e32 v107, v107, v111
	v_cndmask_b32_e64 v102, v108, v102, s[4:5]
	v_cndmask_b32_e64 v108, v110, v112, s[6:7]
	v_cndmask_b32_e64 v110, v103, v101, s[6:7]
	s_waitcnt lgkmcnt(0)
	v_add_f32_e32 v102, v102, v113
	v_cndmask_b32_e64 v101, v101, v103, s[6:7]
	ds_bpermute_b32 v103, v100, v110
	v_cndmask_b32_e64 v110, v109, v107, s[6:7]
	ds_bpermute_b32 v110, v100, v110
	v_cndmask_b32_e64 v111, v106, v102, s[6:7]
	ds_bpermute_b32 v114, v100, v114
	ds_bpermute_b32 v111, v100, v111
	s_waitcnt lgkmcnt(3)
	v_add_f32_e32 v103, v101, v103
	v_cndmask_b32_e64 v101, v107, v109, s[6:7]
	s_waitcnt lgkmcnt(2)
	v_add_f32_e32 v107, v101, v110
	v_cndmask_b32_e64 v101, v102, v106, s[6:7]
	v_cmp_lt_i32_e32 vcc, v221, v218
	s_waitcnt lgkmcnt(1)
	v_add_f32_e32 v108, v108, v114
	s_waitcnt lgkmcnt(0)
	v_add_f32_e32 v102, v101, v111
	v_cndmask_b32_e32 v101, v217, v221, vcc
	v_lshlrev_b32_e32 v101, 2, v101
	v_cndmask_b32_e64 v106, v108, v107, s[8:9]
	v_cndmask_b32_e64 v109, v103, v102, s[8:9]
	ds_bpermute_b32 v106, v101, v106
	ds_bpermute_b32 v109, v101, v109
	v_cndmask_b32_e64 v107, v107, v108, s[8:9]
	v_cndmask_b32_e64 v102, v102, v103, s[8:9]
	v_cmp_lt_i32_e32 vcc, v220, v218
	s_waitcnt lgkmcnt(1)
	v_add_f32_e32 v122, v107, v106
	s_waitcnt lgkmcnt(0)
	v_add_f32_e32 v103, v102, v109
	v_cndmask_b32_e32 v102, v217, v220, vcc
	v_lshlrev_b32_e32 v102, 2, v102
	v_cndmask_b32_e64 v106, v122, v103, s[10:11]
	ds_bpermute_b32 v123, v102, v106
	ds_read_u16 v113, v86 offset:57344
	ds_read_u16 v114, v86 offset:58368
	ds_read_u16 v115, v86 offset:59392
	ds_read_u16 v116, v86 offset:60416
	ds_read_u16 v117, v86 offset:61440
	ds_read_u16 v118, v86 offset:62464
	ds_read_u16 v119, v86 offset:63488
	ds_read_u16 v120, v86 offset:64512
	ds_read_u16 v106, v86 offset:50176
	ds_read_u16 v107, v86 offset:51200
	ds_read_u16 v108, v86 offset:52224
	ds_read_u16 v109, v86 offset:53248
	ds_read_u16 v110, v86 offset:54272
	ds_read_u16 v111, v86 offset:55296
	ds_read_u16 v112, v86 offset:56320
	ds_read_u16 v121, v86 offset:49152
	v_cndmask_b32_e64 v103, v103, v122, s[10:11]
	v_cmp_lt_i32_e32 vcc, v219, v218
	s_waitcnt lgkmcnt(14)
	v_add_f32_e32 v122, v103, v123
	v_cndmask_b32_e32 v103, v217, v219, vcc
	v_lshlrev_b32_e32 v103, 2, v103
	ds_bpermute_b32 v123, v103, v122
	s_and_saveexec_b64 s[14:15], s[12:13]
	s_cbranch_execz .LBB0_433
	s_waitcnt lgkmcnt(0)
	v_add_f32_e32 v122, v122, v123
	ds_write_b32 v91, v122
	s_branch .LBB0_433
